# FoX attention steady steps: the tile's decay-bias reads issued at the head of the step (in flight under the QK^T MFMAs) instead of two at a time in the middle
# speedup vs baseline: 1.0338x; 1.0002x over previous
; __device__ __forceinline__ void biasf(f32x16&p0,f32x16&p1,const __attribute__((address_space(3))) float*p){
;   #pragma unroll
;   for(int j=0;j<4;++j){ const f32x4a a=*(const __attribute__((address_space(3))) f32x4a*)(p+8*j), b=*(const __attribute__((address_space(3))) f32x4a*)(p+32+8*j);
;     p0[4*j]+=a[0];p0[4*j+1]+=a[1];p0[4*j+2]+=a[2];p0[4*j+3]+=a[3]; p1[4*j]+=b[0];p1[4*j+1]+=b[1];p1[4*j+2]+=b[2];p1[4*j+3]+=b[3];
;     asm volatile("":"+v"(p0),"+v"(p1)); __builtin_amdgcn_sched_barrier(0); }
.LBB0_383:
	ds_read_b128 v[222:225], v184
	ds_read_b128 v[226:229], v184 offset:128
	ds_read_b128 v[230:233], v184 offset:32
	ds_read_b128 v[242:245], v184 offset:160
	ds_read_b128 v[246:249], v184 offset:64
	ds_read_b128 v[250:253], v184 offset:192
	v_add_u32_e32 v0, s56, v219
	ds_read_b64_tr_b16 v[176:177], v0 offset:24576
	ds_read_b64_tr_b16 v[178:179], v0 offset:25088
	v_add_f32_e32 v2, v64, v65
	v_add_f32_e32 v2, v66, v2
	v_add_f32_e32 v2, v67, v2
	v_add_f32_e32 v2, v68, v2
	v_add_f32_e32 v2, v69, v2
	v_cvt_pk_bf16_f32 v132, v64, v65
	v_cvt_pk_bf16_f32 v133, v66, v67
	s_waitcnt lgkmcnt(9)
	v_mfma_f32_32x32x16_bf16 v[80:95], v[172:175], v[140:143], 0
	ds_read_b64_tr_b16 v[172:173], v0 offset:28672
	ds_read_b64_tr_b16 v[174:175], v0 offset:29184
	v_add_f32_e32 v2, v70, v2
	v_add_f32_e32 v2, v71, v2
	v_add_f32_e32 v2, v72, v2
	v_add_f32_e32 v2, v73, v2
	v_cvt_pk_bf16_f32 v134, v68, v69
	v_cvt_pk_bf16_f32 v135, v70, v71
	s_waitcnt lgkmcnt(10)
	v_mfma_f32_32x32x16_bf16 v[96:111], v[168:171], v[140:143], 0
	ds_read_b64_tr_b16 v[168:169], v0 offset:25600
	ds_read_b64_tr_b16 v[170:171], v0 offset:26112
	v_add_f32_e32 v2, v74, v2
	v_add_f32_e32 v2, v75, v2
	v_add_f32_e32 v2, v76, v2
	v_add_f32_e32 v2, v77, v2
	v_cvt_pk_bf16_f32 v124, v72, v73
	v_cvt_pk_bf16_f32 v125, v74, v75
	s_waitcnt lgkmcnt(11)
	v_mfma_f32_32x32x16_bf16 v[80:95], v[164:167], v[136:139], v[80:95]
	ds_read_b64_tr_b16 v[164:165], v0 offset:29696
	ds_read_b64_tr_b16 v[166:167], v0 offset:30208
	v_add_f32_e32 v2, v78, v2
	v_add_f32_e32 v2, v79, v2
	v_add_f32_e32 v2, v48, v2
	v_add_f32_e32 v2, v49, v2
	v_cvt_pk_bf16_f32 v126, v76, v77
	v_cvt_pk_bf16_f32 v127, v78, v79
	s_waitcnt lgkmcnt(12)
	v_mfma_f32_32x32x16_bf16 v[96:111], v[160:163], v[136:139], v[96:111]
	ds_read_b64_tr_b16 v[160:161], v0 offset:26624
	ds_read_b64_tr_b16 v[162:163], v0 offset:27136
	v_add_f32_e32 v2, v50, v2
	v_add_f32_e32 v2, v51, v2
	v_add_f32_e32 v2, v52, v2
	v_add_f32_e32 v2, v53, v2
	v_cvt_pk_bf16_f32 v116, v48, v49
	v_cvt_pk_bf16_f32 v117, v50, v51
	s_waitcnt lgkmcnt(13)
	v_mfma_f32_32x32x16_bf16 v[80:95], v[156:159], v[128:131], v[80:95]
	ds_read_b64_tr_b16 v[10:11], v0 offset:30720
	ds_read_b64_tr_b16 v[12:13], v0 offset:31232
	v_add_f32_e32 v2, v54, v2
	v_add_f32_e32 v2, v55, v2
	v_add_f32_e32 v2, v56, v2
	v_add_f32_e32 v2, v57, v2
	v_cvt_pk_bf16_f32 v118, v52, v53
	v_cvt_pk_bf16_f32 v119, v54, v55
	s_waitcnt lgkmcnt(14)
	v_mfma_f32_32x32x16_bf16 v[96:111], v[148:151], v[128:131], v[96:111]
	ds_read_b64_tr_b16 v[6:7], v0 offset:27648
	ds_read_b64_tr_b16 v[8:9], v0 offset:28160
	v_add_f32_e32 v2, v58, v2
	v_add_f32_e32 v2, v59, v2
	v_add_f32_e32 v2, v60, v2
	v_add_f32_e32 v14, v61, v2
	v_cvt_pk_bf16_f32 v112, v56, v57
	v_cvt_pk_bf16_f32 v113, v58, v59
	s_waitcnt lgkmcnt(14)
	v_mfma_f32_32x32x16_bf16 v[80:95], v[152:155], v[120:123], v[80:95]
	ds_read_b64_tr_b16 v[2:3], v0 offset:31744
	ds_read_b64_tr_b16 v[4:5], v0 offset:32256
	v_add_f32_e32 v0, v62, v14
	v_add_f32_e32 v0, v63, v0
	v_add_f32_e32 v0, 0, v0
	v_cvt_pk_bf16_f32 v114, v60, v61
	v_cvt_pk_bf16_f32 v115, v62, v63
	v_mfma_f32_32x32x16_bf16 v[96:111], v[144:147], v[120:123], v[96:111]
	v_lshl_add_u64 v[14:15], v[182:183], 0, s[44:45]
	s_add_i32 s40, s43, s77
	s_mov_b32 s56, m0
	s_mov_b32 m0, s40
	s_nop 0
	global_load_lds_dwordx4 v[14:15], off
	s_mov_b32 m0, s56
	v_lshl_add_u64 v[14:15], v[180:181], 0, s[44:45]
	s_add_i32 s40, s41, s81
	s_mov_b32 s56, m0
	s_mov_b32 m0, s40
	s_nop 0
	global_load_lds_dwordx4 v[14:15], off
	s_mov_b32 m0, s56
	ds_read_b128 v[48:51], v184 offset:96
	ds_read_b128 v[52:55], v184 offset:224
	s_waitcnt lgkmcnt(2)
	v_pk_add_f32 v[80:81], v[80:81], v[222:223]
	v_pk_add_f32 v[82:83], v[82:83], v[224:225]
	v_pk_add_f32 v[96:97], v[96:97], v[226:227]
	v_pk_add_f32 v[98:99], v[98:99], v[228:229]
	v_pk_add_f32 v[84:85], v[84:85], v[230:231]
	v_pk_add_f32 v[86:87], v[86:87], v[232:233]
	v_pk_add_f32 v[100:101], v[100:101], v[242:243]
	v_pk_add_f32 v[102:103], v[102:103], v[244:245]
	v_pk_add_f32 v[88:89], v[88:89], v[246:247]
	v_pk_add_f32 v[90:91], v[90:91], v[248:249]
	v_pk_add_f32 v[104:105], v[104:105], v[250:251]
	v_pk_add_f32 v[106:107], v[106:107], v[252:253]
	s_waitcnt lgkmcnt(1)
	v_pk_add_f32 v[92:93], v[92:93], v[48:49]
	v_pk_add_f32 v[94:95], v[94:95], v[50:51]
	s_waitcnt lgkmcnt(0)
	v_pk_add_f32 v[108:109], v[108:109], v[52:53]
	v_pk_add_f32 v[110:111], v[110:111], v[54:55]
	s_nop 0
	s_nop 0
	v_pk_add_f32 v[48:49], v[80:81], v[196:197] op_sel_hi:[1,0] neg_lo:[0,1] neg_hi:[0,1]
	v_pk_add_f32 v[14:15], v[96:97], v[196:197] op_sel_hi:[1,0] neg_lo:[0,1] neg_hi:[0,1]
	v_pk_add_f32 v[66:67], v[82:83], v[196:197] op_sel_hi:[1,0] neg_lo:[0,1] neg_hi:[0,1]
	v_pk_add_f32 v[50:51], v[98:99], v[196:197] op_sel_hi:[1,0] neg_lo:[0,1] neg_hi:[0,1]
	v_max_f32_e32 v64, v48, v49
	v_pk_add_f32 v[68:69], v[84:85], v[196:197] op_sel_hi:[1,0] neg_lo:[0,1] neg_hi:[0,1]
	v_pk_add_f32 v[70:71], v[86:87], v[196:197] op_sel_hi:[1,0] neg_lo:[0,1] neg_hi:[0,1]
	v_max3_f32 v65, v66, v67, v15
	v_max3_f32 v64, v64, v14, v50
	v_pk_add_f32 v[52:53], v[100:101], v[196:197] op_sel_hi:[1,0] neg_lo:[0,1] neg_hi:[0,1]
	v_pk_add_f32 v[54:55], v[102:103], v[196:197] op_sel_hi:[1,0] neg_lo:[0,1] neg_hi:[0,1]
	v_max3_f32 v64, v64, v51, v68
	v_max3_f32 v65, v65, v70, v71
	v_pk_add_f32 v[72:73], v[88:89], v[196:197] op_sel_hi:[1,0] neg_lo:[0,1] neg_hi:[0,1]
	v_pk_add_f32 v[74:75], v[90:91], v[196:197] op_sel_hi:[1,0] neg_lo:[0,1] neg_hi:[0,1]
	v_max3_f32 v64, v64, v69, v52
	v_max3_f32 v65, v65, v54, v55
	v_pk_add_f32 v[56:57], v[104:105], v[196:197] op_sel_hi:[1,0] neg_lo:[0,1] neg_hi:[0,1]
	v_pk_add_f32 v[58:59], v[106:107], v[196:197] op_sel_hi:[1,0] neg_lo:[0,1] neg_hi:[0,1]
	v_max3_f32 v64, v64, v53, v72
	v_max3_f32 v65, v65, v74, v75
	v_pk_add_f32 v[76:77], v[92:93], v[196:197] op_sel_hi:[1,0] neg_lo:[0,1] neg_hi:[0,1]
	v_pk_add_f32 v[78:79], v[94:95], v[196:197] op_sel_hi:[1,0] neg_lo:[0,1] neg_hi:[0,1]
	v_max3_f32 v64, v64, v73, v56
	v_max3_f32 v65, v65, v58, v59
	v_pk_add_f32 v[60:61], v[108:109], v[196:197] op_sel_hi:[1,0] neg_lo:[0,1] neg_hi:[0,1]
	v_pk_add_f32 v[62:63], v[110:111], v[196:197] op_sel_hi:[1,0] neg_lo:[0,1] neg_hi:[0,1]
	v_max3_f32 v64, v64, v57, v76
	v_max3_f32 v65, v65, v78, v79
	v_max3_f32 v64, v64, v77, v60
	v_max3_f32 v65, v65, v62, v63
	v_max3_f32 v64, v64, v61, v65
	v_mov_b32_e32 v65, v64
	s_nop 1
	v_permlane32_swap_b32_e32 v64, v65
	v_max_f32_e32 v65, v65, v65
	v_max_f32_e32 v64, v64, v64
	v_max_f32_e32 v64, v64, v65
	v_cmp_lt_f32_e32 vcc, s88, v64
	s_cmp_lg_u64 vcc, 0
	v_add_f32_e32 v0, v220, v0
	s_cselect_b64 s[56:57], -1, 0
	s_cbranch_vccnz .LBB0_391

; __device__ __forceinline__ void biasf(f32x16&p0,f32x16&p1,const __attribute__((address_space(3))) float*p){
;   #pragma unroll
;   for(int j=0;j<4;++j){ const f32x4a a=*(const __attribute__((address_space(3))) f32x4a*)(p+8*j), b=*(const __attribute__((address_space(3))) f32x4a*)(p+32+8*j);
;     p0[4*j]+=a[0];p0[4*j+1]+=a[1];p0[4*j+2]+=a[2];p0[4*j+3]+=a[3]; p1[4*j]+=b[0];p1[4*j+1]+=b[1];p1[4*j+2]+=b[2];p1[4*j+3]+=b[3];
;     asm volatile("":"+v"(p0),"+v"(p1)); __builtin_amdgcn_sched_barrier(0); }
.LBB0_386:
	ds_read_b128 v[222:225], v184 offset:256
	ds_read_b128 v[226:229], v184 offset:384
	ds_read_b128 v[230:233], v184 offset:288
	ds_read_b128 v[242:245], v184 offset:416
	ds_read_b128 v[246:249], v184 offset:320
	ds_read_b128 v[250:253], v184 offset:448
	s_add_i32 s40, s41, 0x2000
	s_cmpk_lg_i32 s41, 0x4000
	s_cselect_b32 s80, s40, 0
	v_add_u32_e32 v4, s43, v219
	ds_read_b64_tr_b16 v[160:161], v4 offset:24576
	ds_read_b64_tr_b16 v[162:163], v4 offset:25088
	v_add_f32_e32 v2, v64, v65
	v_add_f32_e32 v2, v66, v2
	v_add_f32_e32 v2, v67, v2
	v_add_f32_e32 v2, v68, v2
	v_add_f32_e32 v2, v69, v2
	v_cvt_pk_bf16_f32 v132, v64, v65
	v_cvt_pk_bf16_f32 v133, v66, v67
	s_waitcnt lgkmcnt(9)
	v_mfma_f32_32x32x16_bf16 v[80:95], v[80:83], v[140:143], 0
	ds_read_b64_tr_b16 v[156:157], v4 offset:28672
	ds_read_b64_tr_b16 v[158:159], v4 offset:29184
	v_add_f32_e32 v2, v70, v2
	v_add_f32_e32 v2, v71, v2
	v_add_f32_e32 v2, v72, v2
	v_add_f32_e32 v2, v73, v2
	v_cvt_pk_bf16_f32 v134, v68, v69
	v_cvt_pk_bf16_f32 v135, v70, v71
	s_waitcnt lgkmcnt(10)
	v_mfma_f32_32x32x16_bf16 v[96:111], v[96:99], v[140:143], 0
	ds_read_b64_tr_b16 v[152:153], v4 offset:25600
	ds_read_b64_tr_b16 v[154:155], v4 offset:26112
	v_add_f32_e32 v2, v74, v2
	v_add_f32_e32 v2, v75, v2
	v_add_f32_e32 v2, v76, v2
	v_add_f32_e32 v2, v77, v2
	v_cvt_pk_bf16_f32 v124, v72, v73
	v_cvt_pk_bf16_f32 v125, v74, v75
	s_waitcnt lgkmcnt(11)
	v_mfma_f32_32x32x16_bf16 v[80:95], v[148:151], v[136:139], v[80:95]
	ds_read_b64_tr_b16 v[148:149], v4 offset:29696
	ds_read_b64_tr_b16 v[150:151], v4 offset:30208
	v_add_f32_e32 v2, v78, v2
	v_add_f32_e32 v2, v79, v2
	v_add_f32_e32 v2, v48, v2
	v_add_f32_e32 v2, v49, v2
	v_cvt_pk_bf16_f32 v126, v76, v77
	v_cvt_pk_bf16_f32 v127, v78, v79
	s_waitcnt lgkmcnt(12)
	v_mfma_f32_32x32x16_bf16 v[96:111], v[144:147], v[136:139], v[96:111]
	ds_read_b64_tr_b16 v[144:145], v4 offset:26624
	ds_read_b64_tr_b16 v[146:147], v4 offset:27136
	v_add_f32_e32 v2, v50, v2
	v_add_f32_e32 v2, v51, v2
	v_add_f32_e32 v2, v52, v2
	v_add_f32_e32 v2, v53, v2
	v_cvt_pk_bf16_f32 v116, v48, v49
	v_cvt_pk_bf16_f32 v117, v50, v51
	s_waitcnt lgkmcnt(13)
	v_mfma_f32_32x32x16_bf16 v[80:95], v[176:179], v[128:131], v[80:95]
	ds_read_b64_tr_b16 v[10:11], v4 offset:30720
	ds_read_b64_tr_b16 v[12:13], v4 offset:31232
	v_add_f32_e32 v2, v54, v2
	v_add_f32_e32 v2, v55, v2
	v_add_f32_e32 v2, v56, v2
	v_add_f32_e32 v2, v57, v2
	v_cvt_pk_bf16_f32 v118, v52, v53
	v_cvt_pk_bf16_f32 v119, v54, v55
	s_waitcnt lgkmcnt(14)
	v_mfma_f32_32x32x16_bf16 v[96:111], v[168:171], v[128:131], v[96:111]
	ds_read_b64_tr_b16 v[6:7], v4 offset:27648
	ds_read_b64_tr_b16 v[8:9], v4 offset:28160
	v_add_f32_e32 v2, v58, v2
	v_add_f32_e32 v2, v59, v2
	v_add_f32_e32 v2, v60, v2
	v_add_f32_e32 v14, v61, v2
	v_cvt_pk_bf16_f32 v112, v56, v57
	v_cvt_pk_bf16_f32 v113, v58, v59
	s_waitcnt lgkmcnt(14)
	v_mfma_f32_32x32x16_bf16 v[80:95], v[172:175], v[120:123], v[80:95]
	ds_read_b64_tr_b16 v[2:3], v4 offset:31744
	ds_read_b64_tr_b16 v[4:5], v4 offset:32256
	v_add_f32_e32 v14, v62, v14
	v_add_f32_e32 v14, v63, v14
	v_add_f32_e32 v64, 0, v14
	v_cvt_pk_bf16_f32 v114, v60, v61
	v_cvt_pk_bf16_f32 v115, v62, v63
	v_mfma_f32_32x32x16_bf16 v[96:111], v[164:167], v[120:123], v[96:111]
	s_add_i32 s40, s41, s77
	s_mov_b32 s43, m0
	s_mov_b32 m0, s40
	s_nop 0
	global_load_lds_dwordx4 v[182:183], off
	s_mov_b32 m0, s43
	s_add_i32 s40, s80, s81
	s_mov_b32 s43, m0
	s_mov_b32 m0, s40
	s_nop 0
	global_load_lds_dwordx4 v[180:181], off
	s_mov_b32 m0, s43
	ds_read_b128 v[48:51], v184 offset:352
	ds_read_b128 v[52:55], v184 offset:480
	s_waitcnt lgkmcnt(2)
	v_pk_add_f32 v[80:81], v[80:81], v[222:223]
	v_pk_add_f32 v[82:83], v[82:83], v[224:225]
	v_pk_add_f32 v[96:97], v[96:97], v[226:227]
	v_pk_add_f32 v[98:99], v[98:99], v[228:229]
	v_pk_add_f32 v[84:85], v[84:85], v[230:231]
	v_pk_add_f32 v[86:87], v[86:87], v[232:233]
	v_pk_add_f32 v[100:101], v[100:101], v[242:243]
	v_pk_add_f32 v[102:103], v[102:103], v[244:245]
	v_pk_add_f32 v[88:89], v[88:89], v[246:247]
	v_pk_add_f32 v[90:91], v[90:91], v[248:249]
	v_pk_add_f32 v[104:105], v[104:105], v[250:251]
	v_pk_add_f32 v[106:107], v[106:107], v[252:253]
	s_waitcnt lgkmcnt(1)
	v_pk_add_f32 v[92:93], v[92:93], v[48:49]
	v_pk_add_f32 v[94:95], v[94:95], v[50:51]
	s_waitcnt lgkmcnt(0)
	v_pk_add_f32 v[108:109], v[108:109], v[52:53]
	v_pk_add_f32 v[110:111], v[110:111], v[54:55]
	s_nop 0
	s_nop 0
	v_pk_add_f32 v[48:49], v[80:81], v[196:197] op_sel_hi:[1,0] neg_lo:[0,1] neg_hi:[0,1]
	v_pk_add_f32 v[14:15], v[96:97], v[196:197] op_sel_hi:[1,0] neg_lo:[0,1] neg_hi:[0,1]
	v_pk_add_f32 v[66:67], v[82:83], v[196:197] op_sel_hi:[1,0] neg_lo:[0,1] neg_hi:[0,1]
	v_pk_add_f32 v[50:51], v[98:99], v[196:197] op_sel_hi:[1,0] neg_lo:[0,1] neg_hi:[0,1]
	v_max_f32_e32 v65, v48, v49
	v_pk_add_f32 v[68:69], v[84:85], v[196:197] op_sel_hi:[1,0] neg_lo:[0,1] neg_hi:[0,1]
	v_pk_add_f32 v[70:71], v[86:87], v[196:197] op_sel_hi:[1,0] neg_lo:[0,1] neg_hi:[0,1]
	v_max3_f32 v80, v66, v67, v15
	v_max3_f32 v65, v65, v14, v50
	v_pk_add_f32 v[52:53], v[100:101], v[196:197] op_sel_hi:[1,0] neg_lo:[0,1] neg_hi:[0,1]
	v_pk_add_f32 v[54:55], v[102:103], v[196:197] op_sel_hi:[1,0] neg_lo:[0,1] neg_hi:[0,1]
	v_max3_f32 v65, v65, v51, v68
	v_max3_f32 v80, v80, v70, v71
	v_pk_add_f32 v[72:73], v[88:89], v[196:197] op_sel_hi:[1,0] neg_lo:[0,1] neg_hi:[0,1]
	v_pk_add_f32 v[74:75], v[90:91], v[196:197] op_sel_hi:[1,0] neg_lo:[0,1] neg_hi:[0,1]
	v_max3_f32 v65, v65, v69, v52
	v_max3_f32 v80, v80, v54, v55
	v_pk_add_f32 v[56:57], v[104:105], v[196:197] op_sel_hi:[1,0] neg_lo:[0,1] neg_hi:[0,1]
	v_pk_add_f32 v[58:59], v[106:107], v[196:197] op_sel_hi:[1,0] neg_lo:[0,1] neg_hi:[0,1]
	v_max3_f32 v65, v65, v53, v72
	v_max3_f32 v80, v80, v74, v75
	v_pk_add_f32 v[76:77], v[92:93], v[196:197] op_sel_hi:[1,0] neg_lo:[0,1] neg_hi:[0,1]
	v_pk_add_f32 v[78:79], v[94:95], v[196:197] op_sel_hi:[1,0] neg_lo:[0,1] neg_hi:[0,1]
	v_max3_f32 v65, v65, v73, v56
	v_max3_f32 v80, v80, v58, v59
	v_pk_add_f32 v[60:61], v[108:109], v[196:197] op_sel_hi:[1,0] neg_lo:[0,1] neg_hi:[0,1]
	v_pk_add_f32 v[62:63], v[110:111], v[196:197] op_sel_hi:[1,0] neg_lo:[0,1] neg_hi:[0,1]
	v_max3_f32 v65, v65, v57, v76
	v_max3_f32 v80, v80, v78, v79
	v_max3_f32 v65, v65, v77, v60
	v_max3_f32 v80, v80, v62, v63
	v_add_f32_e32 v220, v0, v64
	v_max3_f32 v0, v65, v61, v80
	v_mov_b32_e32 v64, v0
	s_nop 1
	v_permlane32_swap_b32_e32 v0, v64
	v_max_f32_e32 v64, v64, v64
	v_max_f32_e32 v0, v0, v0
	v_max_f32_e32 v0, v0, v64
	v_cmp_lt_f32_e32 vcc, s88, v0
	s_cmp_lg_u64 vcc, 0
	s_cselect_b64 s[56:57], -1, 0
	s_cbranch_vccnz .LBB0_394

; __device__ __forceinline__ void biasf(f32x16&p0,f32x16&p1,const __attribute__((address_space(3))) float*p){
;   #pragma unroll
;   for(int j=0;j<4;++j){ const f32x4a a=*(const __attribute__((address_space(3))) f32x4a*)(p+8*j), b=*(const __attribute__((address_space(3))) f32x4a*)(p+32+8*j);
;     p0[4*j]+=a[0];p0[4*j+1]+=a[1];p0[4*j+2]+=a[2];p0[4*j+3]+=a[3]; p1[4*j]+=b[0];p1[4*j+1]+=b[1];p1[4*j+2]+=b[2];p1[4*j+3]+=b[3];
;     asm volatile("":"+v"(p0),"+v"(p1)); __builtin_amdgcn_sched_barrier(0); }
.LBB0_1423:
	ds_read_b128 v[222:225], v184
	ds_read_b128 v[226:229], v184 offset:128
	ds_read_b128 v[230:233], v184 offset:32
	ds_read_b128 v[242:245], v184 offset:160
	ds_read_b128 v[246:249], v184 offset:64
	ds_read_b128 v[250:253], v184 offset:192
	v_add_u32_e32 v0, s54, v219
	ds_read_b64_tr_b16 v[176:177], v0 offset:24576
	ds_read_b64_tr_b16 v[178:179], v0 offset:25088
	v_add_f32_e32 v2, v64, v65
	v_add_f32_e32 v2, v66, v2
	v_add_f32_e32 v2, v67, v2
	v_add_f32_e32 v2, v68, v2
	v_add_f32_e32 v2, v69, v2
	v_cvt_pk_bf16_f32 v132, v64, v65
	v_cvt_pk_bf16_f32 v133, v66, v67
	s_waitcnt lgkmcnt(9)
	v_mfma_f32_32x32x16_bf16 v[80:95], v[172:175], v[140:143], 0
	ds_read_b64_tr_b16 v[172:173], v0 offset:28672
	ds_read_b64_tr_b16 v[174:175], v0 offset:29184
	v_add_f32_e32 v2, v70, v2
	v_add_f32_e32 v2, v71, v2
	v_add_f32_e32 v2, v72, v2
	v_add_f32_e32 v2, v73, v2
	v_cvt_pk_bf16_f32 v134, v68, v69
	v_cvt_pk_bf16_f32 v135, v70, v71
	s_waitcnt lgkmcnt(10)
	v_mfma_f32_32x32x16_bf16 v[96:111], v[168:171], v[140:143], 0
	ds_read_b64_tr_b16 v[168:169], v0 offset:25600
	ds_read_b64_tr_b16 v[170:171], v0 offset:26112
	v_add_f32_e32 v2, v74, v2
	v_add_f32_e32 v2, v75, v2
	v_add_f32_e32 v2, v76, v2
	v_add_f32_e32 v2, v77, v2
	v_cvt_pk_bf16_f32 v124, v72, v73
	v_cvt_pk_bf16_f32 v125, v74, v75
	s_waitcnt lgkmcnt(11)
	v_mfma_f32_32x32x16_bf16 v[80:95], v[164:167], v[136:139], v[80:95]
	ds_read_b64_tr_b16 v[164:165], v0 offset:29696
	ds_read_b64_tr_b16 v[166:167], v0 offset:30208
	v_add_f32_e32 v2, v78, v2
	v_add_f32_e32 v2, v79, v2
	v_add_f32_e32 v2, v48, v2
	v_add_f32_e32 v2, v49, v2
	v_cvt_pk_bf16_f32 v126, v76, v77
	v_cvt_pk_bf16_f32 v127, v78, v79
	s_waitcnt lgkmcnt(12)
	v_mfma_f32_32x32x16_bf16 v[96:111], v[160:163], v[136:139], v[96:111]
	ds_read_b64_tr_b16 v[160:161], v0 offset:26624
	ds_read_b64_tr_b16 v[162:163], v0 offset:27136
	v_add_f32_e32 v2, v50, v2
	v_add_f32_e32 v2, v51, v2
	v_add_f32_e32 v2, v52, v2
	v_add_f32_e32 v2, v53, v2
	v_cvt_pk_bf16_f32 v116, v48, v49
	v_cvt_pk_bf16_f32 v117, v50, v51
	s_waitcnt lgkmcnt(13)
	v_mfma_f32_32x32x16_bf16 v[80:95], v[156:159], v[128:131], v[80:95]
	ds_read_b64_tr_b16 v[10:11], v0 offset:30720
	ds_read_b64_tr_b16 v[12:13], v0 offset:31232
	v_add_f32_e32 v2, v54, v2
	v_add_f32_e32 v2, v55, v2
	v_add_f32_e32 v2, v56, v2
	v_add_f32_e32 v2, v57, v2
	v_cvt_pk_bf16_f32 v118, v52, v53
	v_cvt_pk_bf16_f32 v119, v54, v55
	s_waitcnt lgkmcnt(14)
	v_mfma_f32_32x32x16_bf16 v[96:111], v[148:151], v[128:131], v[96:111]
	ds_read_b64_tr_b16 v[6:7], v0 offset:27648
	ds_read_b64_tr_b16 v[8:9], v0 offset:28160
	v_add_f32_e32 v2, v58, v2
	v_add_f32_e32 v2, v59, v2
	v_add_f32_e32 v2, v60, v2
	v_add_f32_e32 v14, v61, v2
	v_cvt_pk_bf16_f32 v112, v56, v57
	v_cvt_pk_bf16_f32 v113, v58, v59
	s_waitcnt lgkmcnt(14)
	v_mfma_f32_32x32x16_bf16 v[80:95], v[152:155], v[120:123], v[80:95]
	ds_read_b64_tr_b16 v[2:3], v0 offset:31744
	ds_read_b64_tr_b16 v[4:5], v0 offset:32256
	v_add_f32_e32 v0, v62, v14
	v_add_f32_e32 v0, v63, v0
	v_add_f32_e32 v0, 0, v0
	v_cvt_pk_bf16_f32 v114, v60, v61
	v_cvt_pk_bf16_f32 v115, v62, v63
	v_mfma_f32_32x32x16_bf16 v[96:111], v[144:147], v[120:123], v[96:111]
	v_lshl_add_u64 v[14:15], v[182:183], 0, s[42:43]
	s_add_i32 s54, s97, s66
	s_mov_b32 s55, m0
	s_mov_b32 m0, s54
	s_nop 0
	global_load_lds_dwordx4 v[14:15], off
	s_mov_b32 m0, s55
	v_lshl_add_u64 v[14:15], v[180:181], 0, s[42:43]
	s_add_i32 s54, s62, s67
	s_mov_b32 s55, m0
	s_mov_b32 m0, s54
	s_nop 0
	global_load_lds_dwordx4 v[14:15], off
	s_mov_b32 m0, s55
	ds_read_b128 v[48:51], v184 offset:96
	ds_read_b128 v[52:55], v184 offset:224
	s_waitcnt lgkmcnt(2)
	v_pk_add_f32 v[80:81], v[80:81], v[222:223]
	v_pk_add_f32 v[82:83], v[82:83], v[224:225]
	v_pk_add_f32 v[96:97], v[96:97], v[226:227]
	v_pk_add_f32 v[98:99], v[98:99], v[228:229]
	v_pk_add_f32 v[84:85], v[84:85], v[230:231]
	v_pk_add_f32 v[86:87], v[86:87], v[232:233]
	v_pk_add_f32 v[100:101], v[100:101], v[242:243]
	v_pk_add_f32 v[102:103], v[102:103], v[244:245]
	v_pk_add_f32 v[88:89], v[88:89], v[246:247]
	v_pk_add_f32 v[90:91], v[90:91], v[248:249]
	v_pk_add_f32 v[104:105], v[104:105], v[250:251]
	v_pk_add_f32 v[106:107], v[106:107], v[252:253]
	s_waitcnt lgkmcnt(1)
	v_pk_add_f32 v[92:93], v[92:93], v[48:49]
	v_pk_add_f32 v[94:95], v[94:95], v[50:51]
	s_waitcnt lgkmcnt(0)
	v_pk_add_f32 v[108:109], v[108:109], v[52:53]
	v_pk_add_f32 v[110:111], v[110:111], v[54:55]
	s_nop 0
	s_nop 0
	v_pk_add_f32 v[48:49], v[80:81], v[196:197] op_sel_hi:[1,0] neg_lo:[0,1] neg_hi:[0,1]
	v_pk_add_f32 v[14:15], v[96:97], v[196:197] op_sel_hi:[1,0] neg_lo:[0,1] neg_hi:[0,1]
	v_pk_add_f32 v[66:67], v[82:83], v[196:197] op_sel_hi:[1,0] neg_lo:[0,1] neg_hi:[0,1]
	v_pk_add_f32 v[50:51], v[98:99], v[196:197] op_sel_hi:[1,0] neg_lo:[0,1] neg_hi:[0,1]
	v_max_f32_e32 v64, v48, v49
	v_pk_add_f32 v[68:69], v[84:85], v[196:197] op_sel_hi:[1,0] neg_lo:[0,1] neg_hi:[0,1]
	v_pk_add_f32 v[70:71], v[86:87], v[196:197] op_sel_hi:[1,0] neg_lo:[0,1] neg_hi:[0,1]
	v_max3_f32 v65, v66, v67, v15
	v_max3_f32 v64, v64, v14, v50
	v_pk_add_f32 v[52:53], v[100:101], v[196:197] op_sel_hi:[1,0] neg_lo:[0,1] neg_hi:[0,1]
	v_pk_add_f32 v[54:55], v[102:103], v[196:197] op_sel_hi:[1,0] neg_lo:[0,1] neg_hi:[0,1]
	v_max3_f32 v64, v64, v51, v68
	v_max3_f32 v65, v65, v70, v71
	v_pk_add_f32 v[72:73], v[88:89], v[196:197] op_sel_hi:[1,0] neg_lo:[0,1] neg_hi:[0,1]
	v_pk_add_f32 v[74:75], v[90:91], v[196:197] op_sel_hi:[1,0] neg_lo:[0,1] neg_hi:[0,1]
	v_max3_f32 v64, v64, v69, v52
	v_max3_f32 v65, v65, v54, v55
	v_pk_add_f32 v[56:57], v[104:105], v[196:197] op_sel_hi:[1,0] neg_lo:[0,1] neg_hi:[0,1]
	v_pk_add_f32 v[58:59], v[106:107], v[196:197] op_sel_hi:[1,0] neg_lo:[0,1] neg_hi:[0,1]
	v_max3_f32 v64, v64, v53, v72
	v_max3_f32 v65, v65, v74, v75
	v_pk_add_f32 v[76:77], v[92:93], v[196:197] op_sel_hi:[1,0] neg_lo:[0,1] neg_hi:[0,1]
	v_pk_add_f32 v[78:79], v[94:95], v[196:197] op_sel_hi:[1,0] neg_lo:[0,1] neg_hi:[0,1]
	v_max3_f32 v64, v64, v73, v56
	v_max3_f32 v65, v65, v58, v59
	v_pk_add_f32 v[60:61], v[108:109], v[196:197] op_sel_hi:[1,0] neg_lo:[0,1] neg_hi:[0,1]
	v_pk_add_f32 v[62:63], v[110:111], v[196:197] op_sel_hi:[1,0] neg_lo:[0,1] neg_hi:[0,1]
	v_max3_f32 v64, v64, v57, v76
	v_max3_f32 v65, v65, v78, v79
	v_max3_f32 v64, v64, v77, v60
	v_max3_f32 v65, v65, v62, v63
	v_max3_f32 v64, v64, v61, v65
	v_mov_b32_e32 v65, v64
	s_nop 1
	v_permlane32_swap_b32_e32 v64, v65
	v_max_f32_e32 v65, v65, v65
	v_max_f32_e32 v64, v64, v64
	v_max_f32_e32 v64, v64, v65
	v_cmp_lt_f32_e32 vcc, s85, v64
	s_cmp_lg_u64 vcc, 0
	v_add_f32_e32 v0, v220, v0
	s_cselect_b64 s[54:55], -1, 0
	s_cbranch_vccnz .LBB0_1431

; __device__ __forceinline__ void biasf(f32x16&p0,f32x16&p1,const __attribute__((address_space(3))) float*p){
;   #pragma unroll
;   for(int j=0;j<4;++j){ const f32x4a a=*(const __attribute__((address_space(3))) f32x4a*)(p+8*j), b=*(const __attribute__((address_space(3))) f32x4a*)(p+32+8*j);
;     p0[4*j]+=a[0];p0[4*j+1]+=a[1];p0[4*j+2]+=a[2];p0[4*j+3]+=a[3]; p1[4*j]+=b[0];p1[4*j+1]+=b[1];p1[4*j+2]+=b[2];p1[4*j+3]+=b[3];
;     asm volatile("":"+v"(p0),"+v"(p1)); __builtin_amdgcn_sched_barrier(0); }
.LBB0_1426:
	ds_read_b128 v[222:225], v184 offset:256
	ds_read_b128 v[226:229], v184 offset:384
	ds_read_b128 v[230:233], v184 offset:288
	ds_read_b128 v[242:245], v184 offset:416
	ds_read_b128 v[246:249], v184 offset:320
	ds_read_b128 v[250:253], v184 offset:448
	s_add_i32 s54, s62, 0x2000
	s_cmpk_lg_i32 s62, 0x4000
	s_cselect_b32 s95, s54, 0
	v_add_u32_e32 v4, s97, v219
	ds_read_b64_tr_b16 v[160:161], v4 offset:24576
	ds_read_b64_tr_b16 v[162:163], v4 offset:25088
	v_add_f32_e32 v2, v64, v65
	v_add_f32_e32 v2, v66, v2
	v_add_f32_e32 v2, v67, v2
	v_add_f32_e32 v2, v68, v2
	v_add_f32_e32 v2, v69, v2
	v_cvt_pk_bf16_f32 v132, v64, v65
	v_cvt_pk_bf16_f32 v133, v66, v67
	s_waitcnt lgkmcnt(9)
	v_mfma_f32_32x32x16_bf16 v[80:95], v[80:83], v[140:143], 0
	ds_read_b64_tr_b16 v[156:157], v4 offset:28672
	ds_read_b64_tr_b16 v[158:159], v4 offset:29184
	v_add_f32_e32 v2, v70, v2
	v_add_f32_e32 v2, v71, v2
	v_add_f32_e32 v2, v72, v2
	v_add_f32_e32 v2, v73, v2
	v_cvt_pk_bf16_f32 v134, v68, v69
	v_cvt_pk_bf16_f32 v135, v70, v71
	s_waitcnt lgkmcnt(10)
	v_mfma_f32_32x32x16_bf16 v[96:111], v[96:99], v[140:143], 0
	ds_read_b64_tr_b16 v[152:153], v4 offset:25600
	ds_read_b64_tr_b16 v[154:155], v4 offset:26112
	v_add_f32_e32 v2, v74, v2
	v_add_f32_e32 v2, v75, v2
	v_add_f32_e32 v2, v76, v2
	v_add_f32_e32 v2, v77, v2
	v_cvt_pk_bf16_f32 v124, v72, v73
	v_cvt_pk_bf16_f32 v125, v74, v75
	s_waitcnt lgkmcnt(11)
	v_mfma_f32_32x32x16_bf16 v[80:95], v[148:151], v[136:139], v[80:95]
	ds_read_b64_tr_b16 v[148:149], v4 offset:29696
	ds_read_b64_tr_b16 v[150:151], v4 offset:30208
	v_add_f32_e32 v2, v78, v2
	v_add_f32_e32 v2, v79, v2
	v_add_f32_e32 v2, v48, v2
	v_add_f32_e32 v2, v49, v2
	v_cvt_pk_bf16_f32 v126, v76, v77
	v_cvt_pk_bf16_f32 v127, v78, v79
	s_waitcnt lgkmcnt(12)
	v_mfma_f32_32x32x16_bf16 v[96:111], v[144:147], v[136:139], v[96:111]
	ds_read_b64_tr_b16 v[144:145], v4 offset:26624
	ds_read_b64_tr_b16 v[146:147], v4 offset:27136
	v_add_f32_e32 v2, v50, v2
	v_add_f32_e32 v2, v51, v2
	v_add_f32_e32 v2, v52, v2
	v_add_f32_e32 v2, v53, v2
	v_cvt_pk_bf16_f32 v116, v48, v49
	v_cvt_pk_bf16_f32 v117, v50, v51
	s_waitcnt lgkmcnt(13)
	v_mfma_f32_32x32x16_bf16 v[80:95], v[176:179], v[128:131], v[80:95]
	ds_read_b64_tr_b16 v[10:11], v4 offset:30720
	ds_read_b64_tr_b16 v[12:13], v4 offset:31232
	v_add_f32_e32 v2, v54, v2
	v_add_f32_e32 v2, v55, v2
	v_add_f32_e32 v2, v56, v2
	v_add_f32_e32 v2, v57, v2
	v_cvt_pk_bf16_f32 v118, v52, v53
	v_cvt_pk_bf16_f32 v119, v54, v55
	s_waitcnt lgkmcnt(14)
	v_mfma_f32_32x32x16_bf16 v[96:111], v[168:171], v[128:131], v[96:111]
	ds_read_b64_tr_b16 v[6:7], v4 offset:27648
	ds_read_b64_tr_b16 v[8:9], v4 offset:28160
	v_add_f32_e32 v2, v58, v2
	v_add_f32_e32 v2, v59, v2
	v_add_f32_e32 v2, v60, v2
	v_add_f32_e32 v14, v61, v2
	v_cvt_pk_bf16_f32 v112, v56, v57
	v_cvt_pk_bf16_f32 v113, v58, v59
	s_waitcnt lgkmcnt(14)
	v_mfma_f32_32x32x16_bf16 v[80:95], v[172:175], v[120:123], v[80:95]
	ds_read_b64_tr_b16 v[2:3], v4 offset:31744
	ds_read_b64_tr_b16 v[4:5], v4 offset:32256
	v_add_f32_e32 v14, v62, v14
	v_add_f32_e32 v14, v63, v14
	v_add_f32_e32 v64, 0, v14
	v_cvt_pk_bf16_f32 v114, v60, v61
	v_cvt_pk_bf16_f32 v115, v62, v63
	v_mfma_f32_32x32x16_bf16 v[96:111], v[164:167], v[120:123], v[96:111]
	s_add_i32 s54, s62, s66
	s_mov_b32 s55, m0
	s_mov_b32 m0, s54
	s_nop 0
	global_load_lds_dwordx4 v[182:183], off
	s_mov_b32 m0, s55
	s_add_i32 s54, s95, s67
	s_mov_b32 s55, m0
	s_mov_b32 m0, s54
	s_nop 0
	global_load_lds_dwordx4 v[180:181], off
	s_mov_b32 m0, s55
	ds_read_b128 v[48:51], v184 offset:352
	ds_read_b128 v[52:55], v184 offset:480
	s_waitcnt lgkmcnt(2)
	v_pk_add_f32 v[80:81], v[80:81], v[222:223]
	v_pk_add_f32 v[82:83], v[82:83], v[224:225]
	v_pk_add_f32 v[96:97], v[96:97], v[226:227]
	v_pk_add_f32 v[98:99], v[98:99], v[228:229]
	v_pk_add_f32 v[84:85], v[84:85], v[230:231]
	v_pk_add_f32 v[86:87], v[86:87], v[232:233]
	v_pk_add_f32 v[100:101], v[100:101], v[242:243]
	v_pk_add_f32 v[102:103], v[102:103], v[244:245]
	v_pk_add_f32 v[88:89], v[88:89], v[246:247]
	v_pk_add_f32 v[90:91], v[90:91], v[248:249]
	v_pk_add_f32 v[104:105], v[104:105], v[250:251]
	v_pk_add_f32 v[106:107], v[106:107], v[252:253]
	s_waitcnt lgkmcnt(1)
	v_pk_add_f32 v[92:93], v[92:93], v[48:49]
	v_pk_add_f32 v[94:95], v[94:95], v[50:51]
	s_waitcnt lgkmcnt(0)
	v_pk_add_f32 v[108:109], v[108:109], v[52:53]
	v_pk_add_f32 v[110:111], v[110:111], v[54:55]
	s_nop 0
	s_nop 0
	v_pk_add_f32 v[48:49], v[80:81], v[196:197] op_sel_hi:[1,0] neg_lo:[0,1] neg_hi:[0,1]
	v_pk_add_f32 v[14:15], v[96:97], v[196:197] op_sel_hi:[1,0] neg_lo:[0,1] neg_hi:[0,1]
	v_pk_add_f32 v[66:67], v[82:83], v[196:197] op_sel_hi:[1,0] neg_lo:[0,1] neg_hi:[0,1]
	v_pk_add_f32 v[50:51], v[98:99], v[196:197] op_sel_hi:[1,0] neg_lo:[0,1] neg_hi:[0,1]
	v_max_f32_e32 v65, v48, v49
	v_pk_add_f32 v[68:69], v[84:85], v[196:197] op_sel_hi:[1,0] neg_lo:[0,1] neg_hi:[0,1]
	v_pk_add_f32 v[70:71], v[86:87], v[196:197] op_sel_hi:[1,0] neg_lo:[0,1] neg_hi:[0,1]
	v_max3_f32 v80, v66, v67, v15
	v_max3_f32 v65, v65, v14, v50
	v_pk_add_f32 v[52:53], v[100:101], v[196:197] op_sel_hi:[1,0] neg_lo:[0,1] neg_hi:[0,1]
	v_pk_add_f32 v[54:55], v[102:103], v[196:197] op_sel_hi:[1,0] neg_lo:[0,1] neg_hi:[0,1]
	v_max3_f32 v65, v65, v51, v68
	v_max3_f32 v80, v80, v70, v71
	v_pk_add_f32 v[72:73], v[88:89], v[196:197] op_sel_hi:[1,0] neg_lo:[0,1] neg_hi:[0,1]
	v_pk_add_f32 v[74:75], v[90:91], v[196:197] op_sel_hi:[1,0] neg_lo:[0,1] neg_hi:[0,1]
	v_max3_f32 v65, v65, v69, v52
	v_max3_f32 v80, v80, v54, v55
	v_pk_add_f32 v[56:57], v[104:105], v[196:197] op_sel_hi:[1,0] neg_lo:[0,1] neg_hi:[0,1]
	v_pk_add_f32 v[58:59], v[106:107], v[196:197] op_sel_hi:[1,0] neg_lo:[0,1] neg_hi:[0,1]
	v_max3_f32 v65, v65, v53, v72
	v_max3_f32 v80, v80, v74, v75
	v_pk_add_f32 v[76:77], v[92:93], v[196:197] op_sel_hi:[1,0] neg_lo:[0,1] neg_hi:[0,1]
	v_pk_add_f32 v[78:79], v[94:95], v[196:197] op_sel_hi:[1,0] neg_lo:[0,1] neg_hi:[0,1]
	v_max3_f32 v65, v65, v73, v56
	v_max3_f32 v80, v80, v58, v59
	v_pk_add_f32 v[60:61], v[108:109], v[196:197] op_sel_hi:[1,0] neg_lo:[0,1] neg_hi:[0,1]
	v_pk_add_f32 v[62:63], v[110:111], v[196:197] op_sel_hi:[1,0] neg_lo:[0,1] neg_hi:[0,1]
	v_max3_f32 v65, v65, v57, v76
	v_max3_f32 v80, v80, v78, v79
	v_max3_f32 v65, v65, v77, v60
	v_max3_f32 v80, v80, v62, v63
	v_add_f32_e32 v220, v0, v64
	v_max3_f32 v0, v65, v61, v80
	v_mov_b32_e32 v64, v0
	s_nop 1
	v_permlane32_swap_b32_e32 v0, v64
	v_max_f32_e32 v64, v64, v64
	v_max_f32_e32 v0, v0, v0
	v_max_f32_e32 v0, v0, v64
	v_cmp_lt_f32_e32 vcc, s85, v0
	s_cmp_lg_u64 vcc, 0
	s_cselect_b64 s[54:55], -1, 0
	s_cbranch_vccnz .LBB0_1434
